# grid barrier v2: every XCD leader adds to 16 per-XCC replicas of the leader count, all poll own replica (no TOP round trip); phase-4 GEMM workgroups arrive-only at the seam before it
# speedup vs baseline: 1.0193x; 1.0090x over previous
; __device__ __forceinline__ unsigned xb_ld(unsigned* p)              { return __hip_atomic_load(p, __ATOMIC_RELAXED, __HIP_MEMORY_SCOPE_AGENT); }
; __device__ __forceinline__ unsigned xb_add(unsigned* p, unsigned v) { return __hip_atomic_fetch_add(p, v, __ATOMIC_RELAXED, __HIP_MEMORY_SCOPE_AGENT); }
; #define XB_SPIN(cond, bar) do { unsigned _sp = 0; while (cond) { __builtin_amdgcn_s_sleep(1); \
;     if ((++_sp & 255u) == 0u) { if (xb_ld(&(bar)[XB_TMO])) break; if (_sp > XB_SPIN_CAP) { atomicAdd(&(bar)[XB_TMO], 1u); break; } } } } while (0)
; __device__ __forceinline__ void xcd_barrier(const XcdBarrier& b) {
;     asm volatile("s_waitcnt vmcnt(0)" ::: "memory");
;     __syncthreads();
;     if (threadIdx.x == 0) {
;         unsigned* bar = b.bar;
;         __builtin_amdgcn_s_waitcnt(0);
;         unsigned nloc = b.st[0], nx = b.st[1];
;         if (nloc == 0u) { xcd_barrier_complete(bar, b.x, nloc, nx); b.st[0] = nloc; b.st[1] = nx; }
;         const unsigned old = xb_add(&bar[XB_XSUB(b.x)], 1u);
;         const unsigned gen = old / nloc;
;         if (old + 1u == (gen + 1u) * nloc) {
;             __builtin_amdgcn_fence(__ATOMIC_RELEASE, "agent");
;             asm volatile("s_waitcnt vmcnt(0)" ::: "memory");
;             const unsigned og = xb_add(&bar[XB_TOP], 1u);
;             const unsigned tg = og / nx;
;             if (og + 1u == (tg + 1u) * nx) xb_add(&bar[XB_TOPGEN], 1u);
;             else XB_SPIN(xb_ld(&bar[XB_TOPGEN]) == tg, bar);
;             __builtin_amdgcn_fence(__ATOMIC_ACQUIRE, "agent");
;             xb_add(&bar[XB_XGEN(b.x)], 1u);
;             asm volatile("s_waitcnt vmcnt(0)" ::: "memory");
;         } else {
;             XB_SPIN(xb_ld(&bar[XB_XGEN(b.x)]) == gen, bar);
;             __builtin_amdgcn_fence(__ATOMIC_ACQUIRE, "agent");
;             asm volatile("s_waitcnt vmcnt(0)" ::: "memory");
;         }
;     }
;     __syncthreads();
; }
.LBB0_292:
	s_cmp_gt_i32 s51, 2
	s_cselect_b64 s[4:5], -1, 0
	s_and_b64 s[6:7], s[14:15], s[4:5]
	s_andn2_b64 vcc, exec, s[6:7]
	s_cbranch_vccnz .LBB0_346
	s_cmp_eq_u64 s[44:45], 0
	s_cbranch_scc1 .Lgb0_drain
	s_mov_b64 s[8:9], exec
	s_mov_b64 exec, s[44:45]
	s_lshl_b32 s10, s33, 8
	s_add_u32 s12, s46, s10
	s_addc_u32 s13, s47, 0
	v_mov_b32_e32 v1, 0x23fc0
	ds_read2_b32 v[2:3], v1 offset1:1
	v_mov_b32_e32 v0, 0x10000
	global_load_dword v5, v0, s[12:13] sc1
	s_mov_b64 exec, s[8:9]
.Lgb0_drain:
	s_waitcnt vmcnt(0) lgkmcnt(0)
	s_barrier
	s_cmp_eq_u64 s[44:45], 0
	s_cbranch_scc1 .Lgb0_end
	s_mov_b64 exec, s[44:45]
	s_mov_b32 s19, 0
	v_readfirstlane_b32 s15, v2
	v_readfirstlane_b32 s16, v3
	v_readfirstlane_b32 s14, v5
	s_add_i32 s17, s100, -1
	s_mul_i32 s17, s17, s16
	s_cmp_ge_u32 s14, s17
	s_cbranch_scc1 .Lgb0_prev_ok
.Lgb0_prev:
	global_load_dword v5, v0, s[12:13] sc1
	s_waitcnt vmcnt(0)
	v_readfirstlane_b32 s14, v5
	s_cmp_ge_u32 s14, s17
	s_cbranch_scc1 .Lgb0_prev_ok
	s_sleep 1
	s_add_i32 s19, s19, 1
	s_cmp_lt_u32 s19, 20000
	s_cbranch_scc1 .Lgb0_prev
.Lgb0_prev_ok:
	v_mov_b32_e32 v4, 0x1400
	v_mov_b32_e32 v1, 1
	global_atomic_add v4, v4, v1, s[12:13] sc0
	s_add_i32 s17, s100, 1
	s_mul_i32 s18, s17, s15
	s_mul_i32 s17, s100, s16
	s_waitcnt vmcnt(0)
	v_readfirstlane_b32 s14, v4
	s_add_i32 s14, s14, 1
	s_cmp_lg_u32 s14, s18
	s_cbranch_scc1 .Lgb0_wait
	buffer_wbl2 sc1
	s_waitcnt vmcnt(0)
	global_atomic_add v0, v1, s[46:47]
	global_atomic_add v0, v1, s[46:47] offset:256
	global_atomic_add v0, v1, s[46:47] offset:512
	global_atomic_add v0, v1, s[46:47] offset:768
	global_atomic_add v0, v1, s[46:47] offset:1024
	global_atomic_add v0, v1, s[46:47] offset:1280
	global_atomic_add v0, v1, s[46:47] offset:1536
	global_atomic_add v0, v1, s[46:47] offset:1792
	global_atomic_add v0, v1, s[46:47] offset:2048
	global_atomic_add v0, v1, s[46:47] offset:2304
	global_atomic_add v0, v1, s[46:47] offset:2560
	global_atomic_add v0, v1, s[46:47] offset:2816
	global_atomic_add v0, v1, s[46:47] offset:3072
	global_atomic_add v0, v1, s[46:47] offset:3328
	global_atomic_add v0, v1, s[46:47] offset:3584
	global_atomic_add v0, v1, s[46:47] offset:3840
.Lgb0_wait:
.Lgb0_poll:
	global_load_dword v4, v0, s[12:13] sc1
	s_waitcnt vmcnt(0)
	v_readfirstlane_b32 s14, v4
	s_cmp_ge_u32 s14, s17
	s_cbranch_scc1 .Lgb0_acq
	s_sleep 1
	s_add_i32 s19, s19, 1
	s_cmp_lt_u32 s19, 20000
	s_cbranch_scc1 .Lgb0_poll

; __device__ __forceinline__ unsigned xb_ld(unsigned* p)              { return __hip_atomic_load(p, __ATOMIC_RELAXED, __HIP_MEMORY_SCOPE_AGENT); }
; #define XB_SPIN(cond, bar) do { unsigned _sp = 0; while (cond) { __builtin_amdgcn_s_sleep(1); \
;     if ((++_sp & 255u) == 0u) { if (xb_ld(&(bar)[XB_TMO])) break; if (_sp > XB_SPIN_CAP) { atomicAdd(&(bar)[XB_TMO], 1u); break; } } } } while (0)
; __device__ __forceinline__ void xcd_barrier(const XcdBarrier& b) {
;     ...
;         } else {
;             XB_SPIN(xb_ld(&bar[XB_XGEN(b.x)]) == gen, bar);
;             __builtin_amdgcn_fence(__ATOMIC_ACQUIRE, "agent");
;             asm volatile("s_waitcnt vmcnt(0)" ::: "memory");
;         }
;     }
;     __syncthreads();
; }
.Lgb0_done:
	s_waitcnt vmcnt(0)
	s_mov_b64 exec, s[8:9]

; __device__ __forceinline__ void xcd_barrier(const XcdBarrier& b) {
;     asm volatile("s_waitcnt vmcnt(0)" ::: "memory");
;     __syncthreads();
;     if (threadIdx.x == 0) {
;         unsigned* bar = b.bar;
;         __builtin_amdgcn_s_waitcnt(0);
;         unsigned nloc = b.st[0], nx = b.st[1];
.LBB0_392:
	s_cmp_gt_i32 s51, 3
	s_cselect_b64 s[4:5], -1, 0
	s_and_b64 s[6:7], s[10:11], s[4:5]
	s_andn2_b64 vcc, exec, s[6:7]
	s_cbranch_vccnz .LBB0_446
	s_cmp_eq_u64 s[44:45], 0
	s_cbranch_scc1 .Lgb1_drain
	s_mov_b64 s[8:9], exec
	s_mov_b64 exec, s[44:45]
	s_lshl_b32 s10, s33, 8
	s_add_u32 s12, s46, s10
	s_addc_u32 s13, s47, 0
	v_mov_b32_e32 v1, 0x23fc0
	ds_read2_b32 v[2:3], v1 offset1:1
	v_mov_b32_e32 v0, 0x10000
	global_load_dword v5, v0, s[12:13] sc1
	s_mov_b64 exec, s[8:9]

; __device__ __forceinline__ void xcd_barrier(const XcdBarrier& b) {
;     asm volatile("s_waitcnt vmcnt(0)" ::: "memory");
;     __syncthreads();
;     if (threadIdx.x == 0) {
;         unsigned* bar = b.bar;
;         __builtin_amdgcn_s_waitcnt(0);
;         unsigned nloc = b.st[0], nx = b.st[1];
.LBB0_518:
	s_cmp_gt_i32 s51, 4
	s_cselect_b64 s[4:5], -1, 0
	s_and_b64 s[6:7], s[10:11], s[4:5]
	s_andn2_b64 vcc, exec, s[6:7]
	s_cbranch_vccnz .LBB0_572
	s_cmp_eq_u64 s[44:45], 0
	s_cbranch_scc1 .Lgb2_drain
	s_mov_b64 s[8:9], exec
	s_mov_b64 exec, s[44:45]
	s_lshl_b32 s10, s33, 8
	s_add_u32 s12, s46, s10
	s_addc_u32 s13, s47, 0
	v_mov_b32_e32 v1, 0x23fc0
	ds_read2_b32 v[2:3], v1 offset1:1
	v_mov_b32_e32 v0, 0x10000
	global_load_dword v5, v0, s[12:13] sc1
	s_mov_b64 exec, s[8:9]

; __device__ __forceinline__ unsigned xb_ld(unsigned* p)              { return __hip_atomic_load(p, __ATOMIC_RELAXED, __HIP_MEMORY_SCOPE_AGENT); }
; #define XB_SPIN(cond, bar) do { unsigned _sp = 0; while (cond) { __builtin_amdgcn_s_sleep(1); \
;     if ((++_sp & 255u) == 0u) { if (xb_ld(&(bar)[XB_TMO])) break; if (_sp > XB_SPIN_CAP) { atomicAdd(&(bar)[XB_TMO], 1u); break; } } } } while (0)
; __device__ __forceinline__ void xcd_barrier(const XcdBarrier& b) {
;     ...
;         } else {
;             XB_SPIN(xb_ld(&bar[XB_XGEN(b.x)]) == gen, bar);
;             __builtin_amdgcn_fence(__ATOMIC_ACQUIRE, "agent");
;             asm volatile("s_waitcnt vmcnt(0)" ::: "memory");
;         }
; __global__ void __launch_bounds__(NT, 2) hymba_fwd(Args args) {
;     ...
;         const int GA = (G * 3) / 4;
;         if (bx < GA) {
.Lgb2_wait:
	s_mul_i32 s14, s3, 3
	s_lshr_b32 s14, s14, 2
	s_cmp_lt_u32 s2, s14
	s_cbranch_scc1 .Lgb2_done

; __device__ __forceinline__ void xcd_barrier(const XcdBarrier& b) {
;     asm volatile("s_waitcnt vmcnt(0)" ::: "memory");
;     __syncthreads();
;     if (threadIdx.x == 0) {
;         unsigned* bar = b.bar;
;         __builtin_amdgcn_s_waitcnt(0);
;         unsigned nloc = b.st[0], nx = b.st[1];
.LBB0_689:
	s_cmp_gt_i32 s51, 5
	s_cselect_b64 s[4:5], -1, 0
	s_and_b64 s[6:7], s[14:15], s[4:5]
	s_andn2_b64 vcc, exec, s[6:7]
	s_cbranch_vccnz .LBB0_743
	s_cmp_eq_u64 s[44:45], 0
	s_cbranch_scc1 .Lgb3_drain
	s_mov_b64 s[8:9], exec
	s_mov_b64 exec, s[44:45]
	s_lshl_b32 s10, s33, 8
	s_add_u32 s12, s46, s10
	s_addc_u32 s13, s47, 0
	v_mov_b32_e32 v1, 0x23fc0
	ds_read2_b32 v[2:3], v1 offset1:1
	v_mov_b32_e32 v0, 0x10000
	global_load_dword v5, v0, s[12:13] sc1
	s_mov_b64 exec, s[8:9]

; __device__ __forceinline__ void xcd_barrier(const XcdBarrier& b) {
;     asm volatile("s_waitcnt vmcnt(0)" ::: "memory");
;     __syncthreads();
;     if (threadIdx.x == 0) {
;         unsigned* bar = b.bar;
;         __builtin_amdgcn_s_waitcnt(0);
;         unsigned nloc = b.st[0], nx = b.st[1];
.LBB0_939:
	s_cmp_gt_u32 s51, 6
	s_cselect_b64 s[4:5], -1, 0
	s_and_b64 s[4:5], s[62:63], s[4:5]
	s_andn2_b64 vcc, exec, s[4:5]
	s_cbranch_vccnz .LBB0_993
	s_cmp_eq_u64 s[44:45], 0
	s_cbranch_scc1 .Lgb4_drain
	s_mov_b64 s[8:9], exec
	s_mov_b64 exec, s[44:45]
	s_lshl_b32 s10, s33, 8
	s_add_u32 s12, s46, s10
	s_addc_u32 s13, s47, 0
	v_mov_b32_e32 v1, 0x23fc0
	ds_read2_b32 v[2:3], v1 offset1:1
	v_mov_b32_e32 v0, 0x10000
	global_load_dword v5, v0, s[12:13] sc1
	s_mov_b64 exec, s[8:9]

; __device__ __forceinline__ void xcd_barrier(const XcdBarrier& b) {
;     asm volatile("s_waitcnt vmcnt(0)" ::: "memory");
;     __syncthreads();
;     if (threadIdx.x == 0) {
;         unsigned* bar = b.bar;
;         __builtin_amdgcn_s_waitcnt(0);
;         unsigned nloc = b.st[0], nx = b.st[1];
.LBB0_1035:
	s_cmp_gt_i32 s51, 8
	s_cselect_b64 s[4:5], -1, 0
	s_and_b64 s[6:7], s[8:9], s[4:5]
	s_andn2_b64 vcc, exec, s[6:7]
	s_cbranch_vccnz .LBB0_1089
	s_cmp_eq_u64 s[44:45], 0
	s_cbranch_scc1 .Lgb5_drain
	s_mov_b64 s[8:9], exec
	s_mov_b64 exec, s[44:45]
	s_lshl_b32 s10, s33, 8
	s_add_u32 s12, s46, s10
	s_addc_u32 s13, s47, 0
	v_mov_b32_e32 v1, 0x23fc0
	ds_read2_b32 v[2:3], v1 offset1:1
	v_mov_b32_e32 v0, 0x10000
	global_load_dword v5, v0, s[12:13] sc1
	s_mov_b64 exec, s[8:9]

; __device__ __forceinline__ void xcd_barrier(const XcdBarrier& b) {
;     asm volatile("s_waitcnt vmcnt(0)" ::: "memory");
;     __syncthreads();
;     if (threadIdx.x == 0) {
;         unsigned* bar = b.bar;
;         __builtin_amdgcn_s_waitcnt(0);
;         unsigned nloc = b.st[0], nx = b.st[1];
.LBB0_1111:
	s_cmp_gt_u32 s51, 9
	s_cselect_b64 s[4:5], -1, 0
	s_and_b64 s[4:5], s[8:9], s[4:5]
	s_andn2_b64 vcc, exec, s[4:5]
	s_cbranch_vccnz .LBB0_1165
	s_cmp_eq_u64 s[44:45], 0
	s_cbranch_scc1 .Lgb6_drain
	s_mov_b64 s[8:9], exec
	s_mov_b64 exec, s[44:45]
	s_lshl_b32 s10, s33, 8
	s_add_u32 s12, s46, s10
	s_addc_u32 s13, s47, 0
	v_mov_b32_e32 v1, 0x23fc0
	ds_read2_b32 v[2:3], v1 offset1:1
	v_mov_b32_e32 v0, 0x10000
	global_load_dword v5, v0, s[12:13] sc1
	s_mov_b64 exec, s[8:9]

; __device__ __forceinline__ void xcd_barrier(const XcdBarrier& b) {
;     asm volatile("s_waitcnt vmcnt(0)" ::: "memory");
;     __syncthreads();
;     if (threadIdx.x == 0) {
;         unsigned* bar = b.bar;
;         __builtin_amdgcn_s_waitcnt(0);
;         unsigned nloc = b.st[0], nx = b.st[1];
.LBB0_1207:
	s_cmp_gt_i32 s51, 11
	s_cselect_b64 s[4:5], -1, 0
	s_and_b64 s[6:7], s[8:9], s[4:5]
	s_andn2_b64 vcc, exec, s[6:7]
	s_cbranch_vccnz .LBB0_1261
	s_cmp_eq_u64 s[44:45], 0
	s_cbranch_scc1 .Lgb7_drain
	s_mov_b64 s[8:9], exec
	s_mov_b64 exec, s[44:45]
	s_lshl_b32 s10, s33, 8
	s_add_u32 s12, s46, s10
	s_addc_u32 s13, s47, 0
	v_mov_b32_e32 v1, 0x23fc0
	ds_read2_b32 v[2:3], v1 offset1:1
	v_mov_b32_e32 v0, 0x10000
	global_load_dword v5, v0, s[12:13] sc1
	s_mov_b64 exec, s[8:9]

; __device__ __forceinline__ void xcd_barrier(const XcdBarrier& b) {
;     asm volatile("s_waitcnt vmcnt(0)" ::: "memory");
;     __syncthreads();
;     if (threadIdx.x == 0) {
;         unsigned* bar = b.bar;
;         __builtin_amdgcn_s_waitcnt(0);
;         unsigned nloc = b.st[0], nx = b.st[1];
.LBB0_1356:
	s_cmp_gt_i32 s51, 12
	s_cselect_b64 s[4:5], -1, 0
	s_and_b64 s[6:7], s[14:15], s[4:5]
	s_andn2_b64 vcc, exec, s[6:7]
	s_cbranch_vccnz .LBB0_1410
	s_cmp_eq_u64 s[44:45], 0
	s_cbranch_scc1 .Lgb8_drain
	s_mov_b64 s[8:9], exec
	s_mov_b64 exec, s[44:45]
	s_lshl_b32 s10, s33, 8
	s_add_u32 s12, s46, s10
	s_addc_u32 s13, s47, 0
	v_mov_b32_e32 v1, 0x23fc0
	ds_read2_b32 v[2:3], v1 offset1:1
	v_mov_b32_e32 v0, 0x10000
	global_load_dword v5, v0, s[12:13] sc1
	s_mov_b64 exec, s[8:9]
